# grid barrier: all XCD leaders bump every XCD generation word; waiters wait for (gen+1)*nx (TOP ticket round trip removed)
# speedup vs baseline: 1.0143x; 1.0100x over previous
.LBB0_667:
	v_readlane_b32 s8, v254, 34
	s_add_u32 s29, s2, s8
	s_addc_u32 s28, s3, 0
	v_mov_b32_e32 v3, s29
	v_add_co_u32_e32 v4, vcc, 0x1000, v3
	v_mov_b32_e32 v3, s28
	s_nop 0
	v_addc_co_u32_e32 v5, vcc, 0, v3, vcc
	flat_atomic_add v4, v[4:5], v194 offset:1024 sc0
	v_cvt_f32_u32_e32 v3, v2
	v_sub_u32_e32 v5, 0, v2
	v_rcp_iflag_f32_e32 v3, v3
	s_nop 0
	v_mul_f32_e32 v3, 0x4f7ffffe, v3
	v_cvt_u32_f32_e32 v3, v3
	v_mul_lo_u32 v5, v5, v3
	v_mul_hi_u32 v5, v3, v5
	v_add_u32_e32 v3, v3, v5
	s_waitcnt vmcnt(0) lgkmcnt(0)
	v_mul_hi_u32 v3, v4, v3
	v_mul_lo_u32 v5, v3, v2
	v_sub_u32_e32 v5, v4, v5
	v_cmp_ge_u32_e32 vcc, v5, v2
	v_add_u32_e32 v6, 1, v3
	s_nop 0
	v_cndmask_b32_e32 v3, v3, v6, vcc
	v_sub_u32_e32 v6, v5, v2
	v_cndmask_b32_e32 v5, v5, v6, vcc
	v_cmp_ge_u32_e32 vcc, v5, v2
	v_add_u32_e32 v5, 1, v3
	v_add_u32_e32 v6, 1, v4
	v_cndmask_b32_e32 v3, v3, v5, vcc
	v_add_u32_e32 v21, 1, v3
	v_mul_lo_u32 v21, v21, v0
	v_mad_u64_u32 v[4:5], s[8:9], v2, v3, v[2:3]
	v_cmp_ne_u32_e32 vcc, v6, v4
	s_and_saveexec_b64 s[8:9], vcc
	s_xor_b64 s[8:9], exec, s[8:9]
	s_cbranch_execz .LBB0_680
	v_mov_b32_e32 v0, s29
	v_add_co_u32_e32 v4, vcc, 0x2000, v0
	v_mov_b32_e32 v0, s28
	s_nop 0
	v_addc_co_u32_e32 v5, vcc, 0, v0, vcc
	flat_load_dword v0, v[4:5] offset:1024 sc1
	s_add_u32 s12, s29, 0x2400
	s_addc_u32 s13, s28, 0
	s_waitcnt vmcnt(0) lgkmcnt(0)
	v_cmp_ne_u32_e32 vcc, v0, v21
	s_and_saveexec_b64 s[10:11], vcc
	s_cbranch_execz .LBB0_679
	s_mov_b32 s30, 1
	s_mov_b64 s[14:15], 0
	s_branch .LBB0_671

.LBB0_675:
	s_andn2_b64 s[18:19], s[18:19], exec
	s_and_b64 s[24:25], s[24:25], exec
	s_or_b64 s[18:19], s[18:19], s[24:25]
	s_and_saveexec_b64 s[24:25], s[22:23]
	s_cbranch_execz .LBB0_670
	v_mov_b64_e32 v[4:5], s[12:13]
	flat_load_dword v0, v[4:5] sc1
	s_add_i32 s30, s30, 1
	s_or_b64 s[18:19], s[18:19], exec
	s_waitcnt vmcnt(0) lgkmcnt(0)
	v_cmp_eq_u32_e32 vcc, v0, v21
	s_orn2_b64 s[20:21], vcc, exec
	s_branch .LBB0_670

.LBB0_680:
	s_andn2_saveexec_b64 s[8:9], s[8:9]
	s_cbranch_execz .LBB0_696
	buffer_wbl2 sc1
	s_waitcnt vmcnt(0)
	s_add_u32 s16, s72, 0x2400
	s_addc_u32 s17, s73, 0
	v_mov_b32_e32 v6, s16
	v_mov_b32_e32 v7, s17
	flat_atomic_add v[6:7], v194
	flat_atomic_add v[6:7], v194 offset:256
	flat_atomic_add v[6:7], v194 offset:512
	flat_atomic_add v[6:7], v194 offset:768
	flat_atomic_add v[6:7], v194 offset:1024
	flat_atomic_add v[6:7], v194 offset:1280
	flat_atomic_add v[6:7], v194 offset:1536
	flat_atomic_add v[6:7], v194 offset:1792
	flat_atomic_add v[6:7], v194 offset:2048
	flat_atomic_add v[6:7], v194 offset:2304
	flat_atomic_add v[6:7], v194 offset:2560
	flat_atomic_add v[6:7], v194 offset:2816
	flat_atomic_add v[6:7], v194 offset:3072
	flat_atomic_add v[6:7], v194 offset:3328
	flat_atomic_add v[6:7], v194 offset:3584
	flat_atomic_add v[6:7], v194 offset:3840
	s_mov_b64 s[12:13], -1
	s_add_u32 s8, s29, 0x2400
	s_addc_u32 s9, s28, 0
	v_mov_b32_e32 v4, v21
	s_mov_b64 s[10:11], exec
	v_mov_b64_e32 v[2:3], s[8:9]
	flat_load_dword v0, v[2:3] sc1
	s_mov_b64 s[16:17], 0
	s_waitcnt vmcnt(0) lgkmcnt(0)
	v_cmp_ne_u32_e32 vcc, v0, v4
	s_and_saveexec_b64 s[14:15], vcc
	s_cbranch_execz .LBB0_692
	s_add_u32 s12, s2, 0x200
	s_addc_u32 s13, s3, 0
	s_mov_b32 s26, 1
	s_mov_b64 s[2:3], 0
	s_branch .LBB0_685

.LBB0_690:
	v_mov_b64_e32 v[2:3], s[8:9]
	flat_load_dword v0, v[2:3] sc1
	s_add_i32 s26, s26, 1
	s_or_b64 s[20:21], s[20:21], exec
	s_waitcnt vmcnt(0) lgkmcnt(0)
	v_cmp_eq_u32_e32 vcc, v0, v4
	s_orn2_b64 s[18:19], vcc, exec
	s_branch .LBB0_684
